# up GEMM layer-1 last round: 2-way split-K sharing of the 88 leftover units across 176 workgroups
# baseline (speedup 1.0000x reference)
; #define LAS __attribute__((address_space(3)))
; #define PG8_STAGE(bufoff, gbase, voff) do { _Pragma("unroll") for (int _i = 0; _i < 2; ++_i) \
;         __builtin_amdgcn_global_load_lds((const unsigned*)((const char*)(gbase) + (voff)[_i]), (LAS unsigned*)(lds + (bufoff) + ldsw + _i * 8192), 16, 0, 0); } while (0)
; #define PG8_WAIT_V(n) asm volatile("s_waitcnt vmcnt(" #n ")" ::: "memory")
; #define PG8_BAR __builtin_amdgcn_s_barrier()
;     __device__ bool next(int i, Unit& u) const {
;         const long L = (long)i * G + c; if (L >= nwg) return false;
;         int wgid = (int)L; { const int q = nwg / NXCD, r = nwg % NXCD, xcd = wgid % NXCD, off = wgid / NXCD; wgid = (xcd < r ? xcd * (q + 1) : r * (q + 1) + (xcd - r) * q) + off; }
;         const int nig = WGM * nN, gid = wgid / nig, fm = gid * WGM, gsz = (nM - fm) < WGM ? (nM - fm) : WGM;
;         u.pm = fm + ((wgid % nig) % gsz); u.pn = (wgid % nig) / gsz; return true;
; template <class Epi, int LDA, int LDB, int KK>
; __device__ __forceinline__ void gemm_phase(int wv, LAS unsigned char* lds, const Gemm g, const StaticOrder& S, const Epi& E) {
;     ...
;     const char* cA = (const char*)g.A + (size_t)cur.pm * tstepA; const char* cB = (const char*)g.Bt + (size_t)cur.pn * tstepB;
;     if constexpr (Epi::ROWSCALE) { if (wid < 4) __builtin_amdgcn_global_load_lds((const unsigned*)(E.rsq + cur.pm * 256 + wid * 64 + lane), (LAS unsigned*)(lds + 131072 + wid * 256), 4, 0, 0); }
;     PG8_STAGE(PG8_SB(0, 0), cB, voffB); PG8_STAGE(PG8_SA(0, 0), cA, voffA); PG8_STAGE(PG8_SB(0, 1), cB + hstepB, voffB); PG8_STAGE(PG8_SA(0, 1), cA + hstepA, voffA);
;     if (wr == 1) PG8_BAR;
;     PG8_WAIT_V(4); PG8_BAR;
;     PG8_STAGE(PG8_SB(1, 0), cB + kstep, voffB); PG8_STAGE(PG8_SA(1, 0), cA + kstep, voffA); PG8_STAGE(PG8_SB(1, 1), cB + hstepB + kstep, voffB);
;     PG8_WAIT_V(6); PG8_BAR;
;     for (;;) {
;         const bool has_next = S.next(ui + 1, nxt);
;         const char* nA = has_next ? (const char*)g.A + (size_t)nxt.pm * tstepA : cA; const char* nB = has_next ? (const char*)g.Bt + (size_t)nxt.pn * tstepB : cB;
;         if constexpr (Epi::ROWSCALE) { if (has_next && wid < 4) __builtin_amdgcn_global_load_lds((const unsigned*)(E.rsq + nxt.pm * 256 + wid * 64 + lane), (LAS unsigned*)(lds + 131072 + ((ui + 1) % 3) * 1024 + wid * 256), 4, 0, 0); }
.LBB0_760:
	v_and_b32_e32 v20, 15, v5
	v_lshrrev_b32_e32 v5, 1, v5
	v_and_b32_e32 v21, 24, v5
	v_lshlrev_b32_e32 v5, 1, v21
	s_add_u32 s10, s10, 0x8400000
	v_lshl_or_b32 v142, s7, 6, v20
	v_lshl_or_b32 v5, v20, 6, v5
	v_lshlrev_b32_e32 v20, 2, v20
	s_addc_u32 s11, s11, 0
	s_lshl_b32 s14, s7, 13
	v_and_b32_e32 v22, 32, v20
	v_bitop3_b32 v23, v5, s14, v22 bitop3:0xde
	s_lshl_b32 s14, s6, 5
	s_and_b32 s16, s14, 0x60
	s_add_i32 m0, s25, 0x18000
	v_lshl_add_u64 v[12:13], v[12:13], 0, s[58:59]
	s_lshl_b32 s14, s16, 7
	s_waitcnt vmcnt(4)
	s_barrier
	global_load_lds_dwordx4 v[12:13], off
	v_lshl_add_u64 v[10:11], v[10:11], 0, s[58:59]
	s_add_i32 m0, s25, 0x1a000
	s_add_i32 s40, s25, 0x8000
	s_add_i32 s41, s25, 0xa000
	v_bitop3_b32 v143, v5, s14, v22 bitop3:0xde
	global_load_lds_dwordx4 v[10:11], off
	v_lshl_add_u64 v[8:9], v[8:9], 0, s[58:59]
	s_mov_b32 m0, s40
	s_add_u32 s14, s28, 0x80080
	global_load_lds_dwordx4 v[8:9], off
	v_lshl_add_u64 v[6:7], v[6:7], 0, s[58:59]
	s_mov_b32 m0, s41
	s_addc_u32 s15, s29, 0
	global_load_lds_dwordx4 v[6:7], off
	s_add_i32 m0, s25, 0x1c000
	v_lshl_add_u64 v[6:7], s[14:15], 0, v[2:3]
	global_load_lds_dwordx4 v[6:7], off
	v_lshl_add_u64 v[6:7], s[14:15], 0, v[134:135]
	s_add_i32 m0, s25, 0x1e000
	s_lshl_b32 s7, s7, 8
	global_load_lds_dwordx4 v[6:7], off
	s_add_u32 s98, s26, 0x80080
	s_addc_u32 s99, s27, 0
	v_lshl_add_u64 v[218:219], s[98:99], 0, v[0:1]
	s_add_i32 m0, s25, 0xc000
	s_nop 0
	global_load_lds_dwordx4 v[218:219], off
	v_lshl_add_u64 v[218:219], s[98:99], 0, v[132:133]
	s_add_i32 m0, s25, 0xe000
	s_nop 0
	global_load_lds_dwordx4 v[218:219], off
	s_add_i32 s42, 0, 0x20000
	s_and_b32 s14, s31, 0xffffffc0
	s_add_i32 s7, s42, s7
	s_ashr_i32 s15, s14, 31
	s_lshl_b32 s6, s6, 8
	v_add_u32_e32 v144, s7, v20
	s_add_i32 s42, s42, s6
	s_lshl_b64 s[6:7], s[14:15], 2
	s_add_u32 s4, s4, s6
	s_addc_u32 s5, s5, s7
	v_mov_b32_e32 v5, v3
	v_lshl_add_u64 v[136:137], s[4:5], 0, v[4:5]
	v_lshlrev_b32_e32 v4, 15, v17
	v_and_b32_e32 v4, 0xffff0000, v4
	v_lshl_add_u32 v4, v18, 12, v4
	v_and_b32_e32 v5, 1, v17
	v_lshl_or_b32 v4, v5, 6, v4
	v_lshl_add_u32 v138, v19, 1, v4
	v_lshlrev_b32_e32 v4, 15, v14
	v_and_b32_e32 v4, 0xffff0000, v4
	s_waitcnt vmcnt(8)
	v_lshl_add_u32 v4, v15, 12, v4
	v_and_b32_e32 v5, 1, v14
	v_lshl_or_b32 v4, v5, 6, v4
	v_or_b32_e32 v145, s16, v21
	v_mov_b32_e32 v139, v3
	v_lshl_add_u32 v140, v16, 1, v4
	v_mov_b32_e32 v141, v3
	s_mov_b32 s44, 0
	v_add_u32_e32 v146, 0, v23
	s_barrier
	s_mov_b32 s101, 0
.LBB0_761:
	s_mov_b32 s100, s101
	s_add_i32 s43, s44, 1
	s_mul_i32 s4, s43, s49
	s_mul_hi_u32 s5, s43, s48
	s_add_i32 s5, s5, s4
	s_mul_i32 s4, s43, s48
	s_add_u32 s18, s4, s30
	s_addc_u32 s19, s5, s34
	s_mov_b32 s101, 0
	s_cmp_eq_u32 s2, 0
	s_cbranch_scc1 .Lup_h1
	s_cmp_lt_u32 s18, 0xb00
	s_cbranch_scc1 .Lup_h1
	s_sub_u32 s98, s18, 0xb00
	s_cmp_lt_u32 s98, 176
	s_cbranch_scc1 .Lup_h0
	s_movk_i32 s18, 0xb58
	s_branch .Lup_h1
.Lup_h0:
	s_mov_b32 s101, 1
	s_cmp_lt_u32 s98, 88
	s_cbranch_scc1 .Lup_h2
	s_sub_u32 s98, s98, 88
	s_mov_b32 s101, 2
.Lup_h2:
	s_add_u32 s18, s98, 0xb00
.Lup_h1:
	v_mov_b64_e32 v[4:5], 0xb58
	v_cmp_lt_i64_e64 s[6:7], s[18:19], v[4:5]
	v_mov_b64_e32 v[4:5], 0xb57
	v_cmp_gt_i64_e64 s[4:5], s[18:19], v[4:5]
	s_and_b64 vcc, exec, s[4:5]
	s_cbranch_vccnz .LBB0_763
	s_ashr_i32 s14, s18, 31
	s_lshr_b32 s14, s14, 29
	s_add_i32 s14, s18, s14
	s_ashr_i32 s15, s14, 3
	s_and_b32 s14, s14, -8
	s_sub_i32 s14, s18, s14
	s_cmp_lt_i32 s14, 0
	s_movk_i32 s16, 0x16c
	s_cselect_b32 s16, s16, 0x16b
	s_mul_i32 s14, s16, s14
	s_add_i32 s14, s14, s15
	s_mul_hi_i32 s15, s14, 0x2e8ba2e9
	s_lshr_b32 s16, s15, 31
	s_ashr_i32 s15, s15, 6
	s_add_i32 s15, s15, s16
	s_lshl_b32 s16, s15, 3
	s_sub_i32 s17, 0x42, s16
	s_min_i32 s17, s17, 8
	s_abs_i32 s18, s17
	v_cvt_f32_u32_e32 v4, s18
	s_sub_i32 s20, 0, s18
	s_mulk_i32 s15, 0x160
	s_sub_i32 s15, s14, s15
	v_rcp_iflag_f32_e32 v4, v4
	s_abs_i32 s14, s15
	s_xor_b32 s19, s15, s17
	s_ashr_i32 s19, s19, 31
	v_mul_f32_e32 v4, 0x4f7ffffe, v4
	v_cvt_u32_f32_e32 v4, v4
	s_nop 0
	v_readfirstlane_b32 s21, v4
	s_mul_i32 s20, s20, s21
	s_mul_hi_u32 s20, s21, s20
	s_add_i32 s21, s21, s20
	s_mul_hi_u32 s20, s14, s21
	s_mul_i32 s21, s20, s18
	s_sub_i32 s14, s14, s21
	s_add_i32 s45, s20, 1
	s_sub_i32 s21, s14, s18
	s_cmp_ge_u32 s14, s18
	s_cselect_b32 s20, s45, s20
	s_cselect_b32 s14, s21, s14
	s_add_i32 s21, s20, 1
	s_cmp_ge_u32 s14, s18
	s_cselect_b32 s14, s21, s20
	s_xor_b32 s14, s14, s19
	s_sub_i32 s14, s14, s19
	s_mul_i32 s17, s14, s17
	s_sub_i32 s15, s15, s17
	s_add_i32 s16, s15, s16

; #define LAS __attribute__((address_space(3)))
; template <class Epi, int LDA, int LDB, int KK>
; __device__ __forceinline__ void gemm_phase(int wv, LAS unsigned char* lds, const Gemm g, const StaticOrder& S, const Epi& E) {
;     ...
;     for (;;) {
;         const bool has_next = S.next(ui + 1, nxt);
;         const char* nA = has_next ? (const char*)g.A + (size_t)nxt.pm * tstepA : cA; const char* nB = has_next ? (const char*)g.Bt + (size_t)nxt.pn * tstepB : cB;
;         if constexpr (Epi::ROWSCALE) { if (has_next && wid < 4) __builtin_amdgcn_global_load_lds((const unsigned*)(E.rsq + nxt.pm * 256 + wid * 64 + lane), (LAS unsigned*)(lds + 131072 + ((ui + 1) % 3) * 1024 + wid * 256), 4, 0, 0); }
;         for (int seg = 0, t = 0; seg < Epi::NSEG; ++seg) {
;           const int tend = Epi::HAS_MID ? (seg == 0 ? Epi::MID1 : (seg == 1 ? Epi::MID2 : nt)) : nt;
;           for (; t < tend; t += 2) {
;             const bool last = (t == nt - 2);
;             const char* a1 = cA + (size_t)(t + 1) * kstep;
;             const char* a2 = last ? nA : cA + (size_t)(t + 2) * kstep; const char* b2 = last ? nB : cB + (size_t)(t + 2) * kstep;
;             const char* a3 = a2 + kstep; const char* b3 = b2 + kstep;
;             PG8_LDB(B0, 0, 0); PG8_SCHED; PG8_LDA(At, 0, 0); PG8_STAGE(PG8_SA(1, 1), a1 + hstepA, voffA);
;             PG8_WAIT_L(8); PG8_BAR; PG8_WAIT_L(0); PG8_MMA(0, 0, At, B0); PG8_BAR; PG8_SCHED;
;             PG8_LDB(B1, 0, 1); PG8_STAGE(PG8_SB(0, 0), b2, voffB);
;             PG8_BAR; PG8_WAIT_L(0); PG8_MMA(0, 1, At, B1); PG8_BAR;
;             PG8_LDA(At, 0, 1); PG8_STAGE(PG8_SA(0, 0), a2, voffA);
;             PG8_BAR; PG8_WAIT_L(0); PG8_MMA(1, 0, At, B0); PG8_BAR; PG8_SCHED;
;             PG8_STAGE(PG8_SB(0, 1), b2 + hstepB, voffB);
;             PG8_WAIT_V(6); PG8_BAR; PG8_MMA(1, 1, At, B1); PG8_BAR;
;             PG8_LDB(B0, 1, 0); PG8_SCHED; PG8_LDA(At, 1, 0); PG8_STAGE(PG8_SA(0, 1), a2 + hstepA, voffA);
;             PG8_WAIT_L(8); PG8_BAR; PG8_WAIT_L(0); PG8_MMA(0, 0, At, B0); PG8_BAR; PG8_SCHED;
;             PG8_LDB(B1, 1, 1); PG8_STAGE(PG8_SB(1, 0), b3, voffB);
;             PG8_BAR; PG8_WAIT_L(0); PG8_MMA(0, 1, At, B1); PG8_BAR;
;             PG8_LDA(At, 1, 1); PG8_STAGE(PG8_SA(1, 0), a3, voffA);
;             PG8_BAR; PG8_WAIT_L(0); PG8_MMA(1, 0, At, B0); PG8_BAR; PG8_SCHED;
;             PG8_STAGE(PG8_SB(1, 1), b3 + hstepB, voffB);
.LBB0_765:
	s_ashr_i32 s17, s16, 31
	s_lshl_b64 s[18:19], s[16:17], 20
	s_add_u32 s18, s8, s18
	s_addc_u32 s19, s9, s19
	s_cmp_eq_u32 s101, 2
	s_cselect_b32 s98, 0x800, 0
	s_add_u32 s18, s18, s98
	s_addc_u32 s19, s19, 0
	s_and_b64 s[20:21], s[6:7], exec
	s_cselect_b32 s17, s19, s27
	s_cselect_b32 s45, s18, s26
	s_ashr_i32 s15, s14, 31
	s_lshl_b64 s[20:21], s[14:15], 20
	s_add_u32 s20, s35, s20
	s_addc_u32 s21, s36, s21
	s_cmp_eq_u32 s101, 2
	s_cselect_b32 s98, 0x800, 0
	s_add_u32 s20, s20, s98
	s_addc_u32 s21, s21, 0
	s_and_b64 s[6:7], s[6:7], exec
	s_cselect_b32 s15, s21, s29
	s_cselect_b32 s46, s20, s28
	s_add_u32 s47, s28, 0x100
	s_addc_u32 s55, s29, 0
	s_add_u32 s6, s26, 0x80080
	v_mov_b32_e32 v4, 0
	s_addc_u32 s7, s27, 0
	s_mov_b32 s56, -2
	s_cmp_eq_u32 s100, 0
	s_cselect_b32 s56, s56, 14
	v_mov_b32_e32 v5, v4
	v_mov_b32_e32 v6, v4
	v_mov_b32_e32 v7, v4
	v_mov_b32_e32 v8, v4
	v_mov_b32_e32 v9, v4
	v_mov_b32_e32 v10, v4
	v_mov_b32_e32 v11, v4
	v_mov_b32_e32 v20, v4
	v_mov_b32_e32 v21, v4
	v_mov_b32_e32 v22, v4
	v_mov_b32_e32 v23, v4
	v_mov_b32_e32 v24, v4
	v_mov_b32_e32 v25, v4
	v_mov_b32_e32 v26, v4
	v_mov_b32_e32 v27, v4
	v_mov_b32_e32 v36, v4
	v_mov_b32_e32 v37, v4
	v_mov_b32_e32 v38, v4
	v_mov_b32_e32 v39, v4
	v_mov_b32_e32 v40, v4
	v_mov_b32_e32 v41, v4
	v_mov_b32_e32 v42, v4
	v_mov_b32_e32 v43, v4
	v_mov_b32_e32 v52, v4
	v_mov_b32_e32 v53, v4
	v_mov_b32_e32 v54, v4
	v_mov_b32_e32 v55, v4
	v_mov_b32_e32 v56, v4
	v_mov_b32_e32 v57, v4
	v_mov_b32_e32 v58, v4
	v_mov_b32_e32 v59, v4
	v_mov_b32_e32 v12, v4
	v_mov_b32_e32 v13, v4
	v_mov_b32_e32 v14, v4
	v_mov_b32_e32 v15, v4
	v_mov_b32_e32 v16, v4
	v_mov_b32_e32 v17, v4
	v_mov_b32_e32 v18, v4
	v_mov_b32_e32 v19, v4
	v_mov_b32_e32 v28, v4
	v_mov_b32_e32 v29, v4
	v_mov_b32_e32 v30, v4
	v_mov_b32_e32 v31, v4
	v_mov_b32_e32 v32, v4
	v_mov_b32_e32 v33, v4
	v_mov_b32_e32 v34, v4
	v_mov_b32_e32 v35, v4
	v_mov_b32_e32 v44, v4
	v_mov_b32_e32 v45, v4
	v_mov_b32_e32 v46, v4
	v_mov_b32_e32 v47, v4
	v_mov_b32_e32 v48, v4
	v_mov_b32_e32 v49, v4
	v_mov_b32_e32 v50, v4
	v_mov_b32_e32 v51, v4
	v_mov_b32_e32 v60, v4
	v_mov_b32_e32 v61, v4
	v_mov_b32_e32 v62, v4
	v_mov_b32_e32 v63, v4
	v_mov_b32_e32 v64, v4
	v_mov_b32_e32 v65, v4
	v_mov_b32_e32 v66, v4
	v_mov_b32_e32 v67, v4
	v_mov_b32_e32 v68, v4
	v_mov_b32_e32 v69, v4
	v_mov_b32_e32 v70, v4
	v_mov_b32_e32 v71, v4
	v_mov_b32_e32 v72, v4
	v_mov_b32_e32 v73, v4
	v_mov_b32_e32 v74, v4
	v_mov_b32_e32 v75, v4
	v_mov_b32_e32 v84, v4
	v_mov_b32_e32 v85, v4
	v_mov_b32_e32 v86, v4
	v_mov_b32_e32 v87, v4
	v_mov_b32_e32 v88, v4
	v_mov_b32_e32 v89, v4
	v_mov_b32_e32 v90, v4
	v_mov_b32_e32 v91, v4
	v_mov_b32_e32 v100, v4
	v_mov_b32_e32 v101, v4
	v_mov_b32_e32 v102, v4
	v_mov_b32_e32 v103, v4
	v_mov_b32_e32 v104, v4
	v_mov_b32_e32 v105, v4
	v_mov_b32_e32 v106, v4
	v_mov_b32_e32 v107, v4
	v_mov_b32_e32 v116, v4
	v_mov_b32_e32 v117, v4
	v_mov_b32_e32 v118, v4
	v_mov_b32_e32 v119, v4
	v_mov_b32_e32 v120, v4
	v_mov_b32_e32 v121, v4
	v_mov_b32_e32 v122, v4
	v_mov_b32_e32 v123, v4
	v_mov_b32_e32 v76, v4
	v_mov_b32_e32 v77, v4
	v_mov_b32_e32 v78, v4
	v_mov_b32_e32 v79, v4
	v_mov_b32_e32 v80, v4
	v_mov_b32_e32 v81, v4
	v_mov_b32_e32 v82, v4
	v_mov_b32_e32 v83, v4
	v_mov_b32_e32 v92, v4
	v_mov_b32_e32 v93, v4
	v_mov_b32_e32 v94, v4
	v_mov_b32_e32 v95, v4
	v_mov_b32_e32 v96, v4
	v_mov_b32_e32 v97, v4
	v_mov_b32_e32 v98, v4
	v_mov_b32_e32 v99, v4
	v_mov_b32_e32 v108, v4
	v_mov_b32_e32 v109, v4
	v_mov_b32_e32 v110, v4
	v_mov_b32_e32 v111, v4
	v_mov_b32_e32 v112, v4
	v_mov_b32_e32 v113, v4
	v_mov_b32_e32 v114, v4
	v_mov_b32_e32 v115, v4
	v_mov_b32_e32 v124, v4
	v_mov_b32_e32 v125, v4
	v_mov_b32_e32 v126, v4
	v_mov_b32_e32 v127, v4
	v_mov_b32_e32 v128, v4
	v_mov_b32_e32 v129, v4
	v_mov_b32_e32 v130, v4
	v_mov_b32_e32 v131, v4
	v_add_u32_e32 v147, 0x10000, v143
	ds_read_b128 v[148:151], v147 offset:0
	ds_read_b128 v[152:155], v147 offset:2048
	ds_read_b128 v[156:159], v147 offset:16384
	ds_read_b128 v[160:163], v147 offset:18432
	ds_read_b128 v[164:167], v146 offset:0
	ds_read_b128 v[168:171], v146 offset:2048
	ds_read_b128 v[172:175], v146 offset:4096
	ds_read_b128 v[176:179], v146 offset:6144
.Lup_loop:
	s_add_u32 s26, s6, 0xfff80080
	s_addc_u32 s27, s7, -1
	s_cmp_eq_u32 s56, 28
	s_cselect_b32 s29, s17, s27
	s_cselect_b32 s28, s45, s26
	s_cselect_b32 s27, s15, s55
	s_cselect_b32 s26, s46, s47
	s_waitcnt lgkmcnt(0)
	v_mfma_f32_16x16x32_bf16 v[128:131], v[148:151], v[164:167], v[128:131]
	ds_read_b128 v[202:205], v147 offset:1024
	v_mfma_f32_16x16x32_bf16 v[124:127], v[152:155], v[164:167], v[124:127]
	ds_read_b128 v[206:209], v147 offset:3072
	v_mfma_f32_16x16x32_bf16 v[120:123], v[156:159], v[164:167], v[120:123]
	ds_read_b128 v[210:213], v147 offset:17408
	v_mfma_f32_16x16x32_bf16 v[116:119], v[160:163], v[164:167], v[116:119]
	ds_read_b128 v[214:217], v147 offset:19456
	v_mfma_f32_16x16x32_bf16 v[112:115], v[148:151], v[168:171], v[112:115]
	ds_read_b128 v[180:183], v146 offset:1024
	v_mfma_f32_16x16x32_bf16 v[108:111], v[152:155], v[168:171], v[108:111]
	ds_read_b128 v[184:187], v146 offset:3072
	v_mfma_f32_16x16x32_bf16 v[104:107], v[156:159], v[168:171], v[104:107]
	ds_read_b128 v[188:191], v146 offset:5120
	v_mfma_f32_16x16x32_bf16 v[100:103], v[160:163], v[168:171], v[100:103]
	ds_read_b128 v[192:195], v146 offset:7168
	v_mfma_f32_16x16x32_bf16 v[96:99], v[148:151], v[172:175], v[96:99]
	v_mfma_f32_16x16x32_bf16 v[92:95], v[152:155], v[172:175], v[92:95]
	v_mfma_f32_16x16x32_bf16 v[88:91], v[156:159], v[172:175], v[88:91]
	v_mfma_f32_16x16x32_bf16 v[84:87], v[160:163], v[172:175], v[84:87]
	v_mfma_f32_16x16x32_bf16 v[80:83], v[148:151], v[176:179], v[80:83]
	v_mfma_f32_16x16x32_bf16 v[76:79], v[152:155], v[176:179], v[76:79]
	v_mfma_f32_16x16x32_bf16 v[72:75], v[156:159], v[176:179], v[72:75]
	v_mfma_f32_16x16x32_bf16 v[68:71], v[160:163], v[176:179], v[68:71]
	s_waitcnt vmcnt(8) lgkmcnt(0)
	s_barrier
; #define PG8_STAGE(bufoff, gbase, voff) do { _Pragma("unroll") for (int _i = 0; _i < 2; ++_i) \
;         __builtin_amdgcn_global_load_lds((const unsigned*)((const char*)(gbase) + (voff)[_i]), (LAS unsigned*)(lds + (bufoff) + ldsw + _i * 8192), 16, 0, 0); } while (0)
; #define PG8_LDA(dst, b, h) do { _Pragma("unroll") for (int m = 0; m < 4; ++m) _Pragma("unroll") for (int k = 0; k < 2; ++k) dst[m][k] = *(const LAS bf16x8*)(lds + PG8_SA(b, h) + aoff + m * 2048 + k * 1024); } while (0)
; #define PG8_LDB(dst, b, h) do { _Pragma("unroll") for (int n = 0; n < 2; ++n) _Pragma("unroll") for (int k = 0; k < 2; ++k) dst[n][k] = *(const LAS bf16x8*)(lds + PG8_SB(b, h) + boff + n * 2048 + k * 1024); } while (0)
; #define PG8_MMA(ai, bj, At, Bt) do { __builtin_amdgcn_s_setprio(1); _Pragma("unroll") for (int m = 0; m < 4; ++m) _Pragma("unroll") for (int n = 0; n < 2; ++n) _Pragma("unroll") for (int k = 0; k < 2; ++k) \
;         acc[ai][bj][m][n] = __builtin_amdgcn_mfma_f32_16x16x32_bf16(Bt[n][k], At[m][k], acc[ai][bj][m][n], 0, 0, 0); __builtin_amdgcn_s_setprio(0); } while (0)
; #define PG8_WAIT_V(n) asm volatile("s_waitcnt vmcnt(" #n ")" ::: "memory")
; #define PG8_WAIT_L(n) asm volatile("s_waitcnt lgkmcnt(" #n ")" ::: "memory")
; #define PG8_BAR __builtin_amdgcn_s_barrier()
; #define PG8_SCHED __builtin_amdgcn_sched_barrier(0)
; template <class Epi, int LDA, int LDB, int KK>
; __device__ __forceinline__ void gemm_phase(int wv, LAS unsigned char* lds, const Gemm g, const StaticOrder& S, const Epi& E) {
;     ...
;             PG8_WAIT_L(8); PG8_BAR; PG8_WAIT_L(0); PG8_MMA(0, 0, At, B0); PG8_BAR; PG8_SCHED;
;             PG8_LDB(B1, 0, 1); PG8_STAGE(PG8_SB(0, 0), b2, voffB);
;             PG8_BAR; PG8_WAIT_L(0); PG8_MMA(0, 1, At, B1); PG8_BAR;
;             PG8_LDA(At, 0, 1); PG8_STAGE(PG8_SA(0, 0), a2, voffA);
;             PG8_BAR; PG8_WAIT_L(0); PG8_MMA(1, 0, At, B0); PG8_BAR; PG8_SCHED;
;             PG8_STAGE(PG8_SB(0, 1), b2 + hstepB, voffB);
;             PG8_WAIT_V(6); PG8_BAR; PG8_MMA(1, 1, At, B1); PG8_BAR;
;             PG8_LDB(B0, 1, 0); PG8_SCHED; PG8_LDA(At, 1, 0); PG8_STAGE(PG8_SA(0, 1), a2 + hstepA, voffA);
;             PG8_WAIT_L(8); PG8_BAR; PG8_WAIT_L(0); PG8_MMA(0, 0, At, B0); PG8_BAR; PG8_SCHED;
;             PG8_LDB(B1, 1, 1); PG8_STAGE(PG8_SB(1, 0), b3, voffB);
;             PG8_BAR; PG8_WAIT_L(0); PG8_MMA(0, 1, At, B1); PG8_BAR;
	v_mfma_f32_16x16x32_bf16 v[128:131], v[202:205], v[180:183], v[128:131]
	ds_read_b128 v[164:167], v146 offset:16384
	v_mfma_f32_16x16x32_bf16 v[124:127], v[206:209], v[180:183], v[124:127]
	ds_read_b128 v[168:171], v146 offset:18432
	v_mfma_f32_16x16x32_bf16 v[120:123], v[210:213], v[180:183], v[120:123]
	ds_read_b128 v[172:175], v146 offset:20480
	v_mfma_f32_16x16x32_bf16 v[116:119], v[214:217], v[180:183], v[116:119]
	ds_read_b128 v[176:179], v146 offset:22528
	v_mfma_f32_16x16x32_bf16 v[112:115], v[202:205], v[184:187], v[112:115]
	v_lshl_add_u64 v[218:219], s[26:27], 0, v[2:3]
	s_add_i32 m0, s25, 0x10000
	v_mfma_f32_16x16x32_bf16 v[108:111], v[206:209], v[184:187], v[108:111]
	global_load_lds_dwordx4 v[218:219], off
	v_mfma_f32_16x16x32_bf16 v[104:107], v[210:213], v[184:187], v[104:107]
	v_mfma_f32_16x16x32_bf16 v[100:103], v[214:217], v[184:187], v[100:103]
	v_lshl_add_u64 v[218:219], s[26:27], 0, v[134:135]
	s_add_i32 m0, s25, 0x12000
	v_mfma_f32_16x16x32_bf16 v[96:99], v[202:205], v[188:191], v[96:99]
	global_load_lds_dwordx4 v[218:219], off
	v_mfma_f32_16x16x32_bf16 v[92:95], v[206:209], v[188:191], v[92:95]
	v_mfma_f32_16x16x32_bf16 v[88:91], v[210:213], v[188:191], v[88:91]
	v_lshl_add_u64 v[218:219], s[28:29], 0, v[0:1]
	s_mov_b32 m0, s25
	v_mfma_f32_16x16x32_bf16 v[84:87], v[214:217], v[188:191], v[84:87]
	global_load_lds_dwordx4 v[218:219], off
	v_mfma_f32_16x16x32_bf16 v[80:83], v[202:205], v[192:195], v[80:83]
	v_mfma_f32_16x16x32_bf16 v[76:79], v[206:209], v[192:195], v[76:79]
	v_mfma_f32_16x16x32_bf16 v[72:75], v[210:213], v[192:195], v[72:75]
	v_mfma_f32_16x16x32_bf16 v[68:71], v[214:217], v[192:195], v[68:71]
	s_waitcnt lgkmcnt(0)
	v_mfma_f32_16x16x32_bf16 v[64:67], v[148:151], v[164:167], v[64:67]
	ds_read_b128 v[180:183], v146 offset:17408
	v_mfma_f32_16x16x32_bf16 v[60:63], v[152:155], v[164:167], v[60:63]
	ds_read_b128 v[184:187], v146 offset:19456
	v_mfma_f32_16x16x32_bf16 v[56:59], v[156:159], v[164:167], v[56:59]
	ds_read_b128 v[188:191], v146 offset:21504
	v_mfma_f32_16x16x32_bf16 v[52:55], v[160:163], v[164:167], v[52:55]
	ds_read_b128 v[192:195], v146 offset:23552
	v_mfma_f32_16x16x32_bf16 v[48:51], v[148:151], v[168:171], v[48:51]
	v_lshl_add_u64 v[218:219], s[28:29], 0, v[132:133]
	s_add_i32 m0, s25, 0x2000
	v_mfma_f32_16x16x32_bf16 v[44:47], v[152:155], v[168:171], v[44:47]
	global_load_lds_dwordx4 v[218:219], off
	v_mfma_f32_16x16x32_bf16 v[40:43], v[156:159], v[168:171], v[40:43]
	v_mfma_f32_16x16x32_bf16 v[36:39], v[160:163], v[168:171], v[36:39]
	s_add_u32 s98, s26, 0x80000
	s_addc_u32 s99, s27, 0
	v_lshl_add_u64 v[218:219], s[98:99], 0, v[2:3]
	s_add_i32 m0, s25, 0x14000
	v_mfma_f32_16x16x32_bf16 v[32:35], v[148:151], v[172:175], v[32:35]
	global_load_lds_dwordx4 v[218:219], off
	v_mfma_f32_16x16x32_bf16 v[28:31], v[152:155], v[172:175], v[28:31]
	v_mfma_f32_16x16x32_bf16 v[24:27], v[156:159], v[172:175], v[24:27]
	v_lshl_add_u64 v[218:219], s[98:99], 0, v[134:135]
	s_add_i32 m0, s25, 0x16000
	v_mfma_f32_16x16x32_bf16 v[20:23], v[160:163], v[172:175], v[20:23]
	global_load_lds_dwordx4 v[218:219], off
	v_mfma_f32_16x16x32_bf16 v[16:19], v[148:151], v[176:179], v[16:19]
	v_mfma_f32_16x16x32_bf16 v[12:15], v[152:155], v[176:179], v[12:15]
	v_mfma_f32_16x16x32_bf16 v[8:11], v[156:159], v[176:179], v[8:11]
	v_mfma_f32_16x16x32_bf16 v[4:7], v[160:163], v[176:179], v[4:7]
	s_waitcnt vmcnt(8) lgkmcnt(0)
	s_barrier
	v_mfma_f32_16x16x32_bf16 v[64:67], v[202:205], v[180:183], v[64:67]
	ds_read_b128 v[148:151], v147 offset:32768
	v_mfma_f32_16x16x32_bf16 v[60:63], v[206:209], v[180:183], v[60:63]
	ds_read_b128 v[152:155], v147 offset:34816
	v_mfma_f32_16x16x32_bf16 v[56:59], v[210:213], v[180:183], v[56:59]
	ds_read_b128 v[156:159], v147 offset:49152
	v_mfma_f32_16x16x32_bf16 v[52:55], v[214:217], v[180:183], v[52:55]
	ds_read_b128 v[160:163], v147 offset:51200
	v_mfma_f32_16x16x32_bf16 v[48:51], v[202:205], v[184:187], v[48:51]
	ds_read_b128 v[164:167], v146 offset:32768
	v_mfma_f32_16x16x32_bf16 v[44:47], v[206:209], v[184:187], v[44:47]
	ds_read_b128 v[168:171], v146 offset:34816
	v_mfma_f32_16x16x32_bf16 v[40:43], v[210:213], v[184:187], v[40:43]
	ds_read_b128 v[172:175], v146 offset:36864
	v_mfma_f32_16x16x32_bf16 v[36:39], v[214:217], v[184:187], v[36:39]
	ds_read_b128 v[176:179], v146 offset:38912
	v_mfma_f32_16x16x32_bf16 v[32:35], v[202:205], v[188:191], v[32:35]
	s_add_u32 s98, s28, 0x80000
	s_addc_u32 s99, s29, 0
	v_lshl_add_u64 v[218:219], s[98:99], 0, v[0:1]
	s_add_i32 m0, s25, 0x4000
	v_mfma_f32_16x16x32_bf16 v[28:31], v[206:209], v[188:191], v[28:31]
	global_load_lds_dwordx4 v[218:219], off
	v_mfma_f32_16x16x32_bf16 v[24:27], v[210:213], v[188:191], v[24:27]
	v_mfma_f32_16x16x32_bf16 v[20:23], v[214:217], v[188:191], v[20:23]
	v_lshl_add_u64 v[218:219], s[98:99], 0, v[132:133]
	s_add_i32 m0, s25, 0x6000
	v_mfma_f32_16x16x32_bf16 v[16:19], v[202:205], v[192:195], v[16:19]
	global_load_lds_dwordx4 v[218:219], off
	v_mfma_f32_16x16x32_bf16 v[12:15], v[206:209], v[192:195], v[12:15]
	v_mfma_f32_16x16x32_bf16 v[8:11], v[210:213], v[192:195], v[8:11]
	v_mfma_f32_16x16x32_bf16 v[4:7], v[214:217], v[192:195], v[4:7]
	s_add_u32 s26, s26, 0x80
	s_addc_u32 s27, s27, 0
	s_add_u32 s28, s28, 0x80
	s_addc_u32 s29, s29, 0
	s_waitcnt lgkmcnt(0)
	v_mfma_f32_16x16x32_bf16 v[128:131], v[148:151], v[164:167], v[128:131]
	ds_read_b128 v[202:205], v147 offset:33792
	v_mfma_f32_16x16x32_bf16 v[124:127], v[152:155], v[164:167], v[124:127]
	ds_read_b128 v[206:209], v147 offset:35840
	v_mfma_f32_16x16x32_bf16 v[120:123], v[156:159], v[164:167], v[120:123]
	ds_read_b128 v[210:213], v147 offset:50176
	v_mfma_f32_16x16x32_bf16 v[116:119], v[160:163], v[164:167], v[116:119]
	ds_read_b128 v[214:217], v147 offset:52224
	v_mfma_f32_16x16x32_bf16 v[112:115], v[148:151], v[168:171], v[112:115]
	ds_read_b128 v[180:183], v146 offset:33792
	v_mfma_f32_16x16x32_bf16 v[108:111], v[152:155], v[168:171], v[108:111]
	ds_read_b128 v[184:187], v146 offset:35840
	v_mfma_f32_16x16x32_bf16 v[104:107], v[156:159], v[168:171], v[104:107]
	ds_read_b128 v[188:191], v146 offset:37888
	v_mfma_f32_16x16x32_bf16 v[100:103], v[160:163], v[168:171], v[100:103]
	ds_read_b128 v[192:195], v146 offset:39936
	v_mfma_f32_16x16x32_bf16 v[96:99], v[148:151], v[172:175], v[96:99]
	v_mfma_f32_16x16x32_bf16 v[92:95], v[152:155], v[172:175], v[92:95]
	v_mfma_f32_16x16x32_bf16 v[88:91], v[156:159], v[172:175], v[88:91]
	v_mfma_f32_16x16x32_bf16 v[84:87], v[160:163], v[172:175], v[84:87]
	v_mfma_f32_16x16x32_bf16 v[80:83], v[148:151], v[176:179], v[80:83]
	v_mfma_f32_16x16x32_bf16 v[76:79], v[152:155], v[176:179], v[76:79]
	v_mfma_f32_16x16x32_bf16 v[72:75], v[156:159], v[176:179], v[72:75]
	v_mfma_f32_16x16x32_bf16 v[68:71], v[160:163], v[176:179], v[68:71]
	s_waitcnt vmcnt(8) lgkmcnt(0)
	s_barrier
; #define LAS __attribute__((address_space(3)))
; #define PG8_STAGE(bufoff, gbase, voff) do { _Pragma("unroll") for (int _i = 0; _i < 2; ++_i) \
;         __builtin_amdgcn_global_load_lds((const unsigned*)((const char*)(gbase) + (voff)[_i]), (LAS unsigned*)(lds + (bufoff) + ldsw + _i * 8192), 16, 0, 0); } while (0)
; #define PG8_LDA(dst, b, h) do { _Pragma("unroll") for (int m = 0; m < 4; ++m) _Pragma("unroll") for (int k = 0; k < 2; ++k) dst[m][k] = *(const LAS bf16x8*)(lds + PG8_SA(b, h) + aoff + m * 2048 + k * 1024); } while (0)
; #define PG8_MMA(ai, bj, At, Bt) do { __builtin_amdgcn_s_setprio(1); _Pragma("unroll") for (int m = 0; m < 4; ++m) _Pragma("unroll") for (int n = 0; n < 2; ++n) _Pragma("unroll") for (int k = 0; k < 2; ++k) \
;         acc[ai][bj][m][n] = __builtin_amdgcn_mfma_f32_16x16x32_bf16(Bt[n][k], At[m][k], acc[ai][bj][m][n], 0, 0, 0); __builtin_amdgcn_s_setprio(0); } while (0)
; #define PG8_WAIT_V(n) asm volatile("s_waitcnt vmcnt(" #n ")" ::: "memory")
; #define PG8_WAIT_L(n) asm volatile("s_waitcnt lgkmcnt(" #n ")" ::: "memory")
; #define PG8_BAR __builtin_amdgcn_s_barrier()
; #define PG8_SCHED __builtin_amdgcn_sched_barrier(0)
; template <class Epi, int LDA, int LDB, int KK>
; __device__ __forceinline__ void gemm_phase(int wv, LAS unsigned char* lds, const Gemm g, const StaticOrder& S, const Epi& E) {
;     ...
;             PG8_BAR; PG8_WAIT_L(0); PG8_MMA(0, 1, At, B1); PG8_BAR;
;             PG8_LDA(At, 1, 1); PG8_STAGE(PG8_SA(1, 0), a3, voffA);
;             PG8_BAR; PG8_WAIT_L(0); PG8_MMA(1, 0, At, B0); PG8_BAR; PG8_SCHED;
;             PG8_STAGE(PG8_SB(1, 1), b3 + hstepB, voffB);
;             PG8_WAIT_V(6); PG8_BAR; PG8_MMA(1, 1, At, B1); PG8_BAR;
;           }
;           if constexpr (Epi::HAS_MID) { if (seg < Epi::NSEG - 1) E.mid(acc, cur, seg, wr, wc, fr, fq); }
;         }
;         E(acc, cur, wr, wc, fr, fq, (const LAS float*)(lds + 131072 + (ui % 3) * 1024));
	v_mfma_f32_16x16x32_bf16 v[128:131], v[202:205], v[180:183], v[128:131]
	ds_read_b128 v[164:167], v146 offset:49152
	v_mfma_f32_16x16x32_bf16 v[124:127], v[206:209], v[180:183], v[124:127]
	ds_read_b128 v[168:171], v146 offset:51200
	v_mfma_f32_16x16x32_bf16 v[120:123], v[210:213], v[180:183], v[120:123]
	ds_read_b128 v[172:175], v146 offset:53248
	v_mfma_f32_16x16x32_bf16 v[116:119], v[214:217], v[180:183], v[116:119]
	ds_read_b128 v[176:179], v146 offset:55296
	v_mfma_f32_16x16x32_bf16 v[112:115], v[202:205], v[184:187], v[112:115]
	v_lshl_add_u64 v[218:219], s[26:27], 0, v[2:3]
	s_add_i32 m0, s25, 0x18000
	v_mfma_f32_16x16x32_bf16 v[108:111], v[206:209], v[184:187], v[108:111]
	global_load_lds_dwordx4 v[218:219], off
	v_mfma_f32_16x16x32_bf16 v[104:107], v[210:213], v[184:187], v[104:107]
	v_mfma_f32_16x16x32_bf16 v[100:103], v[214:217], v[184:187], v[100:103]
	v_lshl_add_u64 v[218:219], s[26:27], 0, v[134:135]
	s_add_i32 m0, s25, 0x1a000
	v_mfma_f32_16x16x32_bf16 v[96:99], v[202:205], v[188:191], v[96:99]
	global_load_lds_dwordx4 v[218:219], off
	v_mfma_f32_16x16x32_bf16 v[92:95], v[206:209], v[188:191], v[92:95]
	v_mfma_f32_16x16x32_bf16 v[88:91], v[210:213], v[188:191], v[88:91]
	v_lshl_add_u64 v[218:219], s[28:29], 0, v[0:1]
	s_add_i32 m0, s25, 0x8000
	v_mfma_f32_16x16x32_bf16 v[84:87], v[214:217], v[188:191], v[84:87]
	global_load_lds_dwordx4 v[218:219], off
	v_mfma_f32_16x16x32_bf16 v[80:83], v[202:205], v[192:195], v[80:83]
	v_mfma_f32_16x16x32_bf16 v[76:79], v[206:209], v[192:195], v[76:79]
	v_mfma_f32_16x16x32_bf16 v[72:75], v[210:213], v[192:195], v[72:75]
	v_mfma_f32_16x16x32_bf16 v[68:71], v[214:217], v[192:195], v[68:71]
	s_waitcnt lgkmcnt(0)
	v_mfma_f32_16x16x32_bf16 v[64:67], v[148:151], v[164:167], v[64:67]
	ds_read_b128 v[180:183], v146 offset:50176
	v_mfma_f32_16x16x32_bf16 v[60:63], v[152:155], v[164:167], v[60:63]
	ds_read_b128 v[184:187], v146 offset:52224
	v_mfma_f32_16x16x32_bf16 v[56:59], v[156:159], v[164:167], v[56:59]
	ds_read_b128 v[188:191], v146 offset:54272
	v_mfma_f32_16x16x32_bf16 v[52:55], v[160:163], v[164:167], v[52:55]
	ds_read_b128 v[192:195], v146 offset:56320
	v_mfma_f32_16x16x32_bf16 v[48:51], v[148:151], v[168:171], v[48:51]
	v_lshl_add_u64 v[218:219], s[28:29], 0, v[132:133]
	s_add_i32 m0, s25, 0xa000
	v_mfma_f32_16x16x32_bf16 v[44:47], v[152:155], v[168:171], v[44:47]
	global_load_lds_dwordx4 v[218:219], off
	v_mfma_f32_16x16x32_bf16 v[40:43], v[156:159], v[168:171], v[40:43]
	v_mfma_f32_16x16x32_bf16 v[36:39], v[160:163], v[168:171], v[36:39]
	s_add_u32 s98, s26, 0x80000
	s_addc_u32 s99, s27, 0
	v_lshl_add_u64 v[218:219], s[98:99], 0, v[2:3]
	s_add_i32 m0, s25, 0x1c000
	v_mfma_f32_16x16x32_bf16 v[32:35], v[148:151], v[172:175], v[32:35]
	global_load_lds_dwordx4 v[218:219], off
	v_mfma_f32_16x16x32_bf16 v[28:31], v[152:155], v[172:175], v[28:31]
	v_mfma_f32_16x16x32_bf16 v[24:27], v[156:159], v[172:175], v[24:27]
	v_lshl_add_u64 v[218:219], s[98:99], 0, v[134:135]
	s_add_i32 m0, s25, 0x1e000
	v_mfma_f32_16x16x32_bf16 v[20:23], v[160:163], v[172:175], v[20:23]
	global_load_lds_dwordx4 v[218:219], off
	v_mfma_f32_16x16x32_bf16 v[16:19], v[148:151], v[176:179], v[16:19]
	v_mfma_f32_16x16x32_bf16 v[12:15], v[152:155], v[176:179], v[12:15]
	v_mfma_f32_16x16x32_bf16 v[8:11], v[156:159], v[176:179], v[8:11]
	v_mfma_f32_16x16x32_bf16 v[4:7], v[160:163], v[176:179], v[4:7]
	s_waitcnt vmcnt(8) lgkmcnt(0)
	s_barrier
	v_mfma_f32_16x16x32_bf16 v[64:67], v[202:205], v[180:183], v[64:67]
	ds_read_b128 v[148:151], v147 offset:0
	v_mfma_f32_16x16x32_bf16 v[60:63], v[206:209], v[180:183], v[60:63]
	ds_read_b128 v[152:155], v147 offset:2048
	v_mfma_f32_16x16x32_bf16 v[56:59], v[210:213], v[180:183], v[56:59]
	ds_read_b128 v[156:159], v147 offset:16384
	v_mfma_f32_16x16x32_bf16 v[52:55], v[214:217], v[180:183], v[52:55]
	ds_read_b128 v[160:163], v147 offset:18432
	v_mfma_f32_16x16x32_bf16 v[48:51], v[202:205], v[184:187], v[48:51]
	ds_read_b128 v[164:167], v146 offset:0
	v_mfma_f32_16x16x32_bf16 v[44:47], v[206:209], v[184:187], v[44:47]
	ds_read_b128 v[168:171], v146 offset:2048
	v_mfma_f32_16x16x32_bf16 v[40:43], v[210:213], v[184:187], v[40:43]
	ds_read_b128 v[172:175], v146 offset:4096
	v_mfma_f32_16x16x32_bf16 v[36:39], v[214:217], v[184:187], v[36:39]
	ds_read_b128 v[176:179], v146 offset:6144
	v_mfma_f32_16x16x32_bf16 v[32:35], v[202:205], v[188:191], v[32:35]
	s_add_u32 s98, s28, 0x80000
	s_addc_u32 s99, s29, 0
	v_lshl_add_u64 v[218:219], s[98:99], 0, v[0:1]
	s_add_i32 m0, s25, 0xc000
	v_mfma_f32_16x16x32_bf16 v[28:31], v[206:209], v[188:191], v[28:31]
	global_load_lds_dwordx4 v[218:219], off
	v_mfma_f32_16x16x32_bf16 v[24:27], v[210:213], v[188:191], v[24:27]
	v_mfma_f32_16x16x32_bf16 v[20:23], v[214:217], v[188:191], v[20:23]
	v_lshl_add_u64 v[218:219], s[98:99], 0, v[132:133]
	s_add_i32 m0, s25, 0xe000
	v_mfma_f32_16x16x32_bf16 v[16:19], v[202:205], v[192:195], v[16:19]
	global_load_lds_dwordx4 v[218:219], off
	v_mfma_f32_16x16x32_bf16 v[12:15], v[206:209], v[192:195], v[12:15]
	v_mfma_f32_16x16x32_bf16 v[8:11], v[210:213], v[192:195], v[8:11]
	v_mfma_f32_16x16x32_bf16 v[4:7], v[214:217], v[192:195], v[4:7]
	s_add_i32 s56, s56, 2
	s_add_u32 s47, s47, 0x100
	s_addc_u32 s55, s55, 0
	s_add_u32 s6, s6, 0x100
	s_addc_u32 s7, s7, 0
	s_cmp_gt_u32 s56, 29
	s_cbranch_scc0 .Lup_loop
	s_waitcnt lgkmcnt(0)
	s_cmp_eq_u32 s100, 0
	s_cbranch_scc1 .Lut_epi
	s_cmp_eq_u32 s100, 2
	s_cbranch_scc1 .Lut_owner
; #define LAS __attribute__((address_space(3)))
; template <class Epi, int LDA, int LDB, int KK>
; __device__ __forceinline__ void gemm_phase(int wv, LAS unsigned char* lds, const Gemm g, const StaticOrder& S, const Epi& E) {
;     ...
;         E(acc, cur, wr, wc, fr, fq, (const LAS float*)(lds + 131072 + (ui % 3) * 1024));
;         if (!has_next) break;
; #pragma unroll
;         for (int a = 0; a < 2; ++a)
; #pragma unroll
;             for (int b = 0; b < 2; ++b)
; #pragma unroll
;                 for (int m = 0; m < 4; ++m)
; #pragma unroll
;                     for (int n = 0; n < 2; ++n) acc[a][b][m][n] = (f32x4){0.f, 0.f, 0.f, 0.f};
;         cur = nxt; cA = nA; cB = nB; ++ui;
	s_sub_u32 s98, s81, 88
	s_cmp_lt_u32 s81, 88
	s_cselect_b32 s98, s81, s98
	s_lshl_b32 s98, s98, 18
	s_add_u32 s98, s98, 0x16c00000
	s_add_u32 s98, s10, s98
	s_addc_u32 s99, s11, 0
	v_mbcnt_lo_u32_b32 v148, -1, 0
	v_mbcnt_hi_u32_b32 v148, -1, v148
	v_lshl_or_b32 v148, s95, 6, v148
	v_lshlrev_b32_e32 v148, 4, v148
	global_store_dwordx4 v148, v[4:7], s[98:99] sc0 sc1
	v_add_u32_e32 v148, 0x2000, v148
	global_store_dwordx4 v148, v[8:11], s[98:99] sc0 sc1
	v_add_u32_e32 v148, 0x2000, v148
	global_store_dwordx4 v148, v[12:15], s[98:99] sc0 sc1
	v_add_u32_e32 v148, 0x2000, v148
	global_store_dwordx4 v148, v[16:19], s[98:99] sc0 sc1
	v_add_u32_e32 v148, 0x2000, v148
	global_store_dwordx4 v148, v[20:23], s[98:99] sc0 sc1
	v_add_u32_e32 v148, 0x2000, v148
	global_store_dwordx4 v148, v[24:27], s[98:99] sc0 sc1
	v_add_u32_e32 v148, 0x2000, v148
	global_store_dwordx4 v148, v[28:31], s[98:99] sc0 sc1
	v_add_u32_e32 v148, 0x2000, v148
	global_store_dwordx4 v148, v[32:35], s[98:99] sc0 sc1
	v_add_u32_e32 v148, 0x2000, v148
	global_store_dwordx4 v148, v[36:39], s[98:99] sc0 sc1
	v_add_u32_e32 v148, 0x2000, v148
	global_store_dwordx4 v148, v[40:43], s[98:99] sc0 sc1
	v_add_u32_e32 v148, 0x2000, v148
	global_store_dwordx4 v148, v[44:47], s[98:99] sc0 sc1
	v_add_u32_e32 v148, 0x2000, v148
	global_store_dwordx4 v148, v[48:51], s[98:99] sc0 sc1
	v_add_u32_e32 v148, 0x2000, v148
	global_store_dwordx4 v148, v[52:55], s[98:99] sc0 sc1
	v_add_u32_e32 v148, 0x2000, v148
	global_store_dwordx4 v148, v[56:59], s[98:99] sc0 sc1
	v_add_u32_e32 v148, 0x2000, v148
	global_store_dwordx4 v148, v[60:63], s[98:99] sc0 sc1
	v_add_u32_e32 v148, 0x2000, v148
	global_store_dwordx4 v148, v[64:67], s[98:99] sc0 sc1
	v_add_u32_e32 v148, 0x2000, v148
	global_store_dwordx4 v148, v[68:71], s[98:99] sc0 sc1
	v_add_u32_e32 v148, 0x2000, v148
	global_store_dwordx4 v148, v[72:75], s[98:99] sc0 sc1
	v_add_u32_e32 v148, 0x2000, v148
	global_store_dwordx4 v148, v[76:79], s[98:99] sc0 sc1
	v_add_u32_e32 v148, 0x2000, v148
	global_store_dwordx4 v148, v[80:83], s[98:99] sc0 sc1
	v_add_u32_e32 v148, 0x2000, v148
	global_store_dwordx4 v148, v[84:87], s[98:99] sc0 sc1
	v_add_u32_e32 v148, 0x2000, v148
	global_store_dwordx4 v148, v[88:91], s[98:99] sc0 sc1
	v_add_u32_e32 v148, 0x2000, v148
	global_store_dwordx4 v148, v[92:95], s[98:99] sc0 sc1
	v_add_u32_e32 v148, 0x2000, v148
	global_store_dwordx4 v148, v[96:99], s[98:99] sc0 sc1
	v_add_u32_e32 v148, 0x2000, v148
	global_store_dwordx4 v148, v[100:103], s[98:99] sc0 sc1
	v_add_u32_e32 v148, 0x2000, v148
	global_store_dwordx4 v148, v[104:107], s[98:99] sc0 sc1
	v_add_u32_e32 v148, 0x2000, v148
	global_store_dwordx4 v148, v[108:111], s[98:99] sc0 sc1
	v_add_u32_e32 v148, 0x2000, v148
	global_store_dwordx4 v148, v[112:115], s[98:99] sc0 sc1
	v_add_u32_e32 v148, 0x2000, v148
	global_store_dwordx4 v148, v[116:119], s[98:99] sc0 sc1
	v_add_u32_e32 v148, 0x2000, v148
	global_store_dwordx4 v148, v[120:123], s[98:99] sc0 sc1
	v_add_u32_e32 v148, 0x2000, v148
	global_store_dwordx4 v148, v[124:127], s[98:99] sc0 sc1
	v_add_u32_e32 v148, 0x2000, v148
	global_store_dwordx4 v148, v[128:131], s[98:99] sc0 sc1
	s_waitcnt vmcnt(0)
	s_barrier
	s_cmp_lg_u32 s95, 0
	s_cbranch_scc1 .Lut_p_done
	s_sub_u32 s98, s81, 88
	s_cmp_lt_u32 s81, 88
	s_cselect_b32 s98, s81, s98
	s_add_u32 s99, s98, 32
	s_cmp_lt_u32 s98, 64
	s_cselect_b32 s98, s98, s99
	s_lshl_b32 s98, s98, 2
	s_add_u32 s98, s98, 0x201da800
	s_add_u32 s98, s10, s98
	s_addc_u32 s99, s11, 0
	s_mov_b64 exec, 1
	v_mov_b32_e32 v148, 0
	v_mov_b32_e32 v149, 1
	global_atomic_add v148, v149, s[98:99]
	s_mov_b64 exec, -1
.Lut_p_done:
	s_mov_b32 s24, s14
	s_mov_b32 s22, s16
	s_mov_b64 s[28:29], s[20:21]
	s_mov_b64 s[26:27], s[18:19]
	s_mov_b32 s44, s43
	s_and_b64 vcc, exec, s[4:5]
	s_cbranch_vccz .LBB0_761
	s_branch .Lup_end
.Lut_owner:
	s_cmp_lg_u32 s95, 0
	s_cbranch_scc1 .Lut_o_wait
	s_sub_u32 s98, s81, 88
	s_cmp_lt_u32 s81, 88
	s_cselect_b32 s98, s81, s98
	s_add_u32 s99, s98, 32
	s_cmp_lt_u32 s98, 64
	s_cselect_b32 s98, s98, s99
	s_lshl_b32 s98, s98, 2
	s_add_u32 s98, s98, 0x201da800
	s_add_u32 s98, s10, s98
	s_addc_u32 s99, s11, 0
	s_mov_b64 exec, 1
	v_mov_b32_e32 v148, 0
.Lut_poll:
	s_sleep 2
	global_load_dword v149, v148, s[98:99] sc1
	s_waitcnt vmcnt(0)
	v_cmp_gt_u32_e32 vcc, 1, v149
	s_cbranch_vccnz .Lut_poll
	buffer_inv sc1
	s_waitcnt vmcnt(0)
	s_mov_b64 exec, -1
; #define LAS __attribute__((address_space(3)))
; template <class Epi, int LDA, int LDB, int KK>
; __device__ __forceinline__ void gemm_phase(int wv, LAS unsigned char* lds, const Gemm g, const StaticOrder& S, const Epi& E) {
;     ...
;         E(acc, cur, wr, wc, fr, fq, (const LAS float*)(lds + 131072 + (ui % 3) * 1024));
;         if (!has_next) break;
.Lut_o_wait:
	s_barrier
	s_sub_u32 s98, s81, 88
	s_cmp_lt_u32 s81, 88
	s_cselect_b32 s98, s81, s98
	s_lshl_b32 s98, s98, 18
	s_add_u32 s98, s98, 0x16c00000
	s_add_u32 s98, s10, s98
	s_addc_u32 s99, s11, 0
	v_mbcnt_lo_u32_b32 v148, -1, 0
	v_mbcnt_hi_u32_b32 v148, -1, v148
	v_lshl_or_b32 v148, s95, 6, v148
	v_lshlrev_b32_e32 v148, 4, v148
	global_load_dwordx4 v[152:155], v148, s[98:99] sc0 sc1
	v_add_u32_e32 v148, 0x2000, v148
	global_load_dwordx4 v[156:159], v148, s[98:99] sc0 sc1
	v_add_u32_e32 v148, 0x2000, v148
	global_load_dwordx4 v[160:163], v148, s[98:99] sc0 sc1
	v_add_u32_e32 v148, 0x2000, v148
	global_load_dwordx4 v[164:167], v148, s[98:99] sc0 sc1
	v_add_u32_e32 v148, 0x2000, v148
	global_load_dwordx4 v[168:171], v148, s[98:99] sc0 sc1
	v_add_u32_e32 v148, 0x2000, v148
	global_load_dwordx4 v[172:175], v148, s[98:99] sc0 sc1
	v_add_u32_e32 v148, 0x2000, v148
	global_load_dwordx4 v[176:179], v148, s[98:99] sc0 sc1
	v_add_u32_e32 v148, 0x2000, v148
	global_load_dwordx4 v[180:183], v148, s[98:99] sc0 sc1
	v_add_u32_e32 v148, 0x2000, v148
	s_waitcnt vmcnt(7)
	v_pk_add_f32 v[4:5], v[4:5], v[152:153]
	v_pk_add_f32 v[6:7], v[6:7], v[154:155]
	s_waitcnt vmcnt(6)
	v_pk_add_f32 v[8:9], v[8:9], v[156:157]
	v_pk_add_f32 v[10:11], v[10:11], v[158:159]
	s_waitcnt vmcnt(5)
	v_pk_add_f32 v[12:13], v[12:13], v[160:161]
	v_pk_add_f32 v[14:15], v[14:15], v[162:163]
	s_waitcnt vmcnt(4)
	v_pk_add_f32 v[16:17], v[16:17], v[164:165]
	v_pk_add_f32 v[18:19], v[18:19], v[166:167]
	s_waitcnt vmcnt(3)
	v_pk_add_f32 v[20:21], v[20:21], v[168:169]
	v_pk_add_f32 v[22:23], v[22:23], v[170:171]
	s_waitcnt vmcnt(2)
	v_pk_add_f32 v[24:25], v[24:25], v[172:173]
	v_pk_add_f32 v[26:27], v[26:27], v[174:175]
	s_waitcnt vmcnt(1)
	v_pk_add_f32 v[28:29], v[28:29], v[176:177]
	v_pk_add_f32 v[30:31], v[30:31], v[178:179]
	s_waitcnt vmcnt(0)
	v_pk_add_f32 v[32:33], v[32:33], v[180:181]
	v_pk_add_f32 v[34:35], v[34:35], v[182:183]
	global_load_dwordx4 v[152:155], v148, s[98:99] sc0 sc1
	v_add_u32_e32 v148, 0x2000, v148
	global_load_dwordx4 v[156:159], v148, s[98:99] sc0 sc1
	v_add_u32_e32 v148, 0x2000, v148
	global_load_dwordx4 v[160:163], v148, s[98:99] sc0 sc1
	v_add_u32_e32 v148, 0x2000, v148
	global_load_dwordx4 v[164:167], v148, s[98:99] sc0 sc1
	v_add_u32_e32 v148, 0x2000, v148
	global_load_dwordx4 v[168:171], v148, s[98:99] sc0 sc1
	v_add_u32_e32 v148, 0x2000, v148
	global_load_dwordx4 v[172:175], v148, s[98:99] sc0 sc1
	v_add_u32_e32 v148, 0x2000, v148
	global_load_dwordx4 v[176:179], v148, s[98:99] sc0 sc1
	v_add_u32_e32 v148, 0x2000, v148
	global_load_dwordx4 v[180:183], v148, s[98:99] sc0 sc1
	v_add_u32_e32 v148, 0x2000, v148
	s_waitcnt vmcnt(7)
	v_pk_add_f32 v[36:37], v[36:37], v[152:153]
	v_pk_add_f32 v[38:39], v[38:39], v[154:155]
	s_waitcnt vmcnt(6)
	v_pk_add_f32 v[40:41], v[40:41], v[156:157]
	v_pk_add_f32 v[42:43], v[42:43], v[158:159]
	s_waitcnt vmcnt(5)
	v_pk_add_f32 v[44:45], v[44:45], v[160:161]
	v_pk_add_f32 v[46:47], v[46:47], v[162:163]
	s_waitcnt vmcnt(4)
	v_pk_add_f32 v[48:49], v[48:49], v[164:165]
	v_pk_add_f32 v[50:51], v[50:51], v[166:167]
	s_waitcnt vmcnt(3)
	v_pk_add_f32 v[52:53], v[52:53], v[168:169]
	v_pk_add_f32 v[54:55], v[54:55], v[170:171]
	s_waitcnt vmcnt(2)
	v_pk_add_f32 v[56:57], v[56:57], v[172:173]
	v_pk_add_f32 v[58:59], v[58:59], v[174:175]
	s_waitcnt vmcnt(1)
	v_pk_add_f32 v[60:61], v[60:61], v[176:177]
	v_pk_add_f32 v[62:63], v[62:63], v[178:179]
	s_waitcnt vmcnt(0)
	v_pk_add_f32 v[64:65], v[64:65], v[180:181]
	v_pk_add_f32 v[66:67], v[66:67], v[182:183]
	global_load_dwordx4 v[152:155], v148, s[98:99] sc0 sc1
	v_add_u32_e32 v148, 0x2000, v148
	global_load_dwordx4 v[156:159], v148, s[98:99] sc0 sc1
	v_add_u32_e32 v148, 0x2000, v148
	global_load_dwordx4 v[160:163], v148, s[98:99] sc0 sc1
	v_add_u32_e32 v148, 0x2000, v148
	global_load_dwordx4 v[164:167], v148, s[98:99] sc0 sc1
	v_add_u32_e32 v148, 0x2000, v148
	global_load_dwordx4 v[168:171], v148, s[98:99] sc0 sc1
	v_add_u32_e32 v148, 0x2000, v148
	global_load_dwordx4 v[172:175], v148, s[98:99] sc0 sc1
	v_add_u32_e32 v148, 0x2000, v148
	global_load_dwordx4 v[176:179], v148, s[98:99] sc0 sc1
	v_add_u32_e32 v148, 0x2000, v148
	global_load_dwordx4 v[180:183], v148, s[98:99] sc0 sc1
	v_add_u32_e32 v148, 0x2000, v148
	s_waitcnt vmcnt(7)
	v_pk_add_f32 v[68:69], v[68:69], v[152:153]
	v_pk_add_f32 v[70:71], v[70:71], v[154:155]
	s_waitcnt vmcnt(6)
	v_pk_add_f32 v[72:73], v[72:73], v[156:157]
	v_pk_add_f32 v[74:75], v[74:75], v[158:159]
	s_waitcnt vmcnt(5)
	v_pk_add_f32 v[76:77], v[76:77], v[160:161]
	v_pk_add_f32 v[78:79], v[78:79], v[162:163]
	s_waitcnt vmcnt(4)
	v_pk_add_f32 v[80:81], v[80:81], v[164:165]
	v_pk_add_f32 v[82:83], v[82:83], v[166:167]
	s_waitcnt vmcnt(3)
	v_pk_add_f32 v[84:85], v[84:85], v[168:169]
	v_pk_add_f32 v[86:87], v[86:87], v[170:171]
	s_waitcnt vmcnt(2)
	v_pk_add_f32 v[88:89], v[88:89], v[172:173]
	v_pk_add_f32 v[90:91], v[90:91], v[174:175]
	s_waitcnt vmcnt(1)
	v_pk_add_f32 v[92:93], v[92:93], v[176:177]
	v_pk_add_f32 v[94:95], v[94:95], v[178:179]
	s_waitcnt vmcnt(0)
	v_pk_add_f32 v[96:97], v[96:97], v[180:181]
	v_pk_add_f32 v[98:99], v[98:99], v[182:183]
	global_load_dwordx4 v[152:155], v148, s[98:99] sc0 sc1
	v_add_u32_e32 v148, 0x2000, v148
	global_load_dwordx4 v[156:159], v148, s[98:99] sc0 sc1
	v_add_u32_e32 v148, 0x2000, v148
	global_load_dwordx4 v[160:163], v148, s[98:99] sc0 sc1
	v_add_u32_e32 v148, 0x2000, v148
	global_load_dwordx4 v[164:167], v148, s[98:99] sc0 sc1
	v_add_u32_e32 v148, 0x2000, v148
	global_load_dwordx4 v[168:171], v148, s[98:99] sc0 sc1
	v_add_u32_e32 v148, 0x2000, v148
	global_load_dwordx4 v[172:175], v148, s[98:99] sc0 sc1
	v_add_u32_e32 v148, 0x2000, v148
	global_load_dwordx4 v[176:179], v148, s[98:99] sc0 sc1
	v_add_u32_e32 v148, 0x2000, v148
	global_load_dwordx4 v[180:183], v148, s[98:99] sc0 sc1
	s_waitcnt vmcnt(7)
	v_pk_add_f32 v[100:101], v[100:101], v[152:153]
	v_pk_add_f32 v[102:103], v[102:103], v[154:155]
	s_waitcnt vmcnt(6)
	v_pk_add_f32 v[104:105], v[104:105], v[156:157]
	v_pk_add_f32 v[106:107], v[106:107], v[158:159]
	s_waitcnt vmcnt(5)
	v_pk_add_f32 v[108:109], v[108:109], v[160:161]
	v_pk_add_f32 v[110:111], v[110:111], v[162:163]
	s_waitcnt vmcnt(4)
	v_pk_add_f32 v[112:113], v[112:113], v[164:165]
	v_pk_add_f32 v[114:115], v[114:115], v[166:167]
	s_waitcnt vmcnt(3)
	v_pk_add_f32 v[116:117], v[116:117], v[168:169]
	v_pk_add_f32 v[118:119], v[118:119], v[170:171]
	s_waitcnt vmcnt(2)
	v_pk_add_f32 v[120:121], v[120:121], v[172:173]
	v_pk_add_f32 v[122:123], v[122:123], v[174:175]
	s_waitcnt vmcnt(1)
	v_pk_add_f32 v[124:125], v[124:125], v[176:177]
	v_pk_add_f32 v[126:127], v[126:127], v[178:179]
	s_waitcnt vmcnt(0)
	v_pk_add_f32 v[128:129], v[128:129], v[180:181]
	v_pk_add_f32 v[130:131], v[130:131], v[182:183]
; #define LAS __attribute__((address_space(3)))
; __device__ __forceinline__ u32x4 pack8(const f32x4& a, const f32x4& b) { u32x4 w; w.x = pack2(a[0], a[1]); w.y = pack2(a[2], a[3]); w.z = pack2(b[0], b[1]); w.w = pack2(b[2], b[3]); return w; }
;     __device__ __forceinline__ void operator()(AccT& acc, const pg8::Unit& u, int wr, int wc, int fr, int fq, const LAS float* rs) const {
;         int row0 = u.pm * 256 + wr * 64 + fr; asm volatile("" : "+v"(row0)); const int cb = u.pn * 256 + wc * 32 + 8 * fq;
; #pragma unroll
;         for (int ai = 0; ai < 2; ++ai)
; #pragma unroll
;             for (int m = 0; m < 4; ++m) {
;                 const int row = row0 + ai * 128 + m * 16; const float sc = rsqrtf(rs[ai * 128 + wr * 64 + m * 16 + fr] * (1.0f / D) + EPS);
; #pragma unroll
;                 for (int bj = 0; bj < 2; ++bj) *(u32x4*)(z2 + (size_t)row * NUP + cb + bj * 128) = pack8(acc[ai][bj][m][0] * sc, acc[ai][bj][m][1] * sc);
;             }
.Lut_epi:
	s_mul_hi_u32 s6, s44, 0xaaaaaaab
	s_lshr_b32 s6, s6, 1
	s_mul_i32 s6, s6, 3
	s_sub_i32 s6, s44, s6
	v_lshl_add_u32 v147, s22, 8, v142
	v_lshl_add_u32 v148, s6, 10, v144
	ds_read2_b32 v[152:153], v148 offset1:16
	v_lshl_or_b32 v150, s24, 8, v145
	v_ashrrev_i32_e32 v151, 31, v150
	s_mov_b32 s24, s14
	s_mov_b32 s22, s16
	s_waitcnt lgkmcnt(0)
	v_fmamk_f32 v149, v152, 0x3a000000, v220
	v_cmp_gt_f32_e32 vcc, s96, v149
	v_mul_f32_e32 v152, 0x4b800000, v149
	s_mov_b64 s[28:29], s[20:21]
	v_cndmask_b32_e32 v149, v149, v152, vcc
	v_rsq_f32_e32 v149, v149
	s_mov_b64 s[26:27], s[18:19]
	s_mov_b32 s44, s43
	v_mul_f32_e32 v152, 0x45800000, v149
	v_cndmask_b32_e32 v152, v149, v152, vcc
	v_pk_mul_f32 v[130:131], v[130:131], v[152:153] op_sel_hi:[1,0]
	v_pk_mul_f32 v[128:129], v[128:129], v[152:153] op_sel_hi:[1,0]
	v_pk_mul_f32 v[124:125], v[124:125], v[152:153] op_sel_hi:[1,0]
	v_pk_mul_f32 v[126:127], v[126:127], v[152:153] op_sel_hi:[1,0]
	v_cvt_pk_bf16_f32 v128, v128, v129
	v_cvt_pk_bf16_f32 v129, v130, v131
	v_cvt_pk_bf16_f32 v130, v124, v125
	v_mov_b64_e32 v[124:125], s[10:11]
	v_cvt_pk_bf16_f32 v131, v126, v127
	v_mad_i64_i32 v[154:155], s[6:7], v147, s51, v[124:125]
	v_lshlrev_b64 v[126:127], 1, v[150:151]
	v_lshl_add_u64 v[150:151], v[154:155], 0, v[126:127]
	global_store_dwordx4 v[150:151], v[128:131], off
	v_pk_mul_f32 v[120:121], v[120:121], v[152:153] op_sel_hi:[1,0]
	v_pk_mul_f32 v[122:123], v[122:123], v[152:153] op_sel_hi:[1,0]
	v_pk_mul_f32 v[128:129], v[118:119], v[152:153] op_sel_hi:[1,0]
	v_pk_mul_f32 v[118:119], v[116:117], v[152:153] op_sel_hi:[1,0]
	v_cvt_pk_bf16_f32 v116, v120, v121
	v_cvt_pk_bf16_f32 v117, v122, v123
	s_nop 0
	v_cvt_pk_bf16_f32 v118, v118, v119
	v_cvt_pk_bf16_f32 v119, v128, v129
	global_store_dwordx4 v[150:151], v[116:119], off offset:256
	s_nop 1
	v_fmamk_f32 v116, v153, 0x3a000000, v220
	v_cmp_gt_f32_e32 vcc, s96, v116
	v_mul_f32_e32 v118, 0x4b800000, v116
	v_add_u32_e32 v117, 16, v147
	v_cndmask_b32_e32 v116, v116, v118, vcc
	v_rsq_f32_e32 v116, v116
	s_nop 0
	v_mul_f32_e32 v118, 0x45800000, v116
	v_cndmask_b32_e32 v116, v116, v118, vcc
	v_pk_mul_f32 v[112:113], v[112:113], v[116:117] op_sel_hi:[1,0]
	v_pk_mul_f32 v[118:119], v[110:111], v[116:117] op_sel_hi:[1,0]
	v_pk_mul_f32 v[110:111], v[108:109], v[116:117] op_sel_hi:[1,0]
	v_cvt_pk_bf16_f32 v108, v112, v113
	v_mad_i64_i32 v[112:113], s[6:7], v117, s51, v[124:125]
	v_pk_mul_f32 v[114:115], v[114:115], v[116:117] op_sel_hi:[1,0]
	v_lshl_add_u64 v[112:113], v[112:113], 0, v[126:127]
	v_cvt_pk_bf16_f32 v109, v114, v115
	v_cvt_pk_bf16_f32 v110, v110, v111
	v_cvt_pk_bf16_f32 v111, v118, v119
	global_store_dwordx4 v[112:113], v[108:111], off
	v_pk_mul_f32 v[106:107], v[106:107], v[116:117] op_sel_hi:[1,0]
	v_pk_mul_f32 v[104:105], v[104:105], v[116:117] op_sel_hi:[1,0]
	v_pk_mul_f32 v[108:109], v[102:103], v[116:117] op_sel_hi:[1,0]
	v_pk_mul_f32 v[102:103], v[100:101], v[116:117] op_sel_hi:[1,0]
	v_cvt_pk_bf16_f32 v100, v104, v105
	v_cvt_pk_bf16_f32 v101, v106, v107
	v_add_u32_e32 v104, 32, v147
	v_cvt_pk_bf16_f32 v102, v102, v103
	v_cvt_pk_bf16_f32 v103, v108, v109
	global_store_dwordx4 v[112:113], v[100:103], off offset:256
	ds_read2_b32 v[100:101], v148 offset0:32 offset1:48
	s_waitcnt lgkmcnt(0)
	v_fmamk_f32 v100, v100, 0x3a000000, v220
	v_cmp_gt_f32_e32 vcc, s96, v100
	v_mul_f32_e32 v102, 0x4b800000, v100
	s_nop 0
	v_cndmask_b32_e32 v100, v100, v102, vcc
	v_rsq_f32_e32 v100, v100
	s_nop 0
	v_mul_f32_e32 v102, 0x45800000, v100
	v_cndmask_b32_e32 v100, v100, v102, vcc
	v_pk_mul_f32 v[96:97], v[96:97], v[100:101] op_sel_hi:[1,0]
	v_pk_mul_f32 v[102:103], v[94:95], v[100:101] op_sel_hi:[1,0]
	v_pk_mul_f32 v[94:95], v[92:93], v[100:101] op_sel_hi:[1,0]
	v_cvt_pk_bf16_f32 v92, v96, v97
	v_mad_i64_i32 v[96:97], s[6:7], v104, s51, v[124:125]
	v_pk_mul_f32 v[98:99], v[98:99], v[100:101] op_sel_hi:[1,0]
	v_lshl_add_u64 v[96:97], v[96:97], 0, v[126:127]
	v_cvt_pk_bf16_f32 v93, v98, v99
	v_cvt_pk_bf16_f32 v94, v94, v95
	v_cvt_pk_bf16_f32 v95, v102, v103
	global_store_dwordx4 v[96:97], v[92:95], off
	v_pk_mul_f32 v[88:89], v[88:89], v[100:101] op_sel_hi:[1,0]
	v_pk_mul_f32 v[90:91], v[90:91], v[100:101] op_sel_hi:[1,0]
	v_pk_mul_f32 v[92:93], v[86:87], v[100:101] op_sel_hi:[1,0]
	v_pk_mul_f32 v[86:87], v[84:85], v[100:101] op_sel_hi:[1,0]
	v_cvt_pk_bf16_f32 v84, v88, v89
	v_cvt_pk_bf16_f32 v85, v90, v91
	s_nop 0
	v_cvt_pk_bf16_f32 v86, v86, v87
	v_cvt_pk_bf16_f32 v87, v92, v93
	global_store_dwordx4 v[96:97], v[84:87], off offset:256
	s_nop 1
	v_fmamk_f32 v84, v101, 0x3a000000, v220
	v_cmp_gt_f32_e32 vcc, s96, v84
	v_mul_f32_e32 v86, 0x4b800000, v84
	v_add_u32_e32 v85, 48, v147
	v_cndmask_b32_e32 v84, v84, v86, vcc
	v_rsq_f32_e32 v84, v84
	s_nop 0
	v_mul_f32_e32 v86, 0x45800000, v84
	v_cndmask_b32_e32 v84, v84, v86, vcc
	v_pk_mul_f32 v[80:81], v[80:81], v[84:85] op_sel_hi:[1,0]
	v_pk_mul_f32 v[86:87], v[78:79], v[84:85] op_sel_hi:[1,0]
	v_pk_mul_f32 v[78:79], v[76:77], v[84:85] op_sel_hi:[1,0]
	v_cvt_pk_bf16_f32 v76, v80, v81
	v_mad_i64_i32 v[80:81], s[6:7], v85, s51, v[124:125]
	v_pk_mul_f32 v[82:83], v[82:83], v[84:85] op_sel_hi:[1,0]
	v_lshl_add_u64 v[80:81], v[80:81], 0, v[126:127]
	v_cvt_pk_bf16_f32 v77, v82, v83
	v_cvt_pk_bf16_f32 v78, v78, v79
	v_cvt_pk_bf16_f32 v79, v86, v87
	global_store_dwordx4 v[80:81], v[76:79], off
	v_pk_mul_f32 v[74:75], v[74:75], v[84:85] op_sel_hi:[1,0]
	v_pk_mul_f32 v[72:73], v[72:73], v[84:85] op_sel_hi:[1,0]
	v_pk_mul_f32 v[76:77], v[70:71], v[84:85] op_sel_hi:[1,0]
	v_pk_mul_f32 v[70:71], v[68:69], v[84:85] op_sel_hi:[1,0]
	v_cvt_pk_bf16_f32 v68, v72, v73
	v_cvt_pk_bf16_f32 v69, v74, v75
	v_add_u32_e32 v72, 0x80, v147
	v_cvt_pk_bf16_f32 v70, v70, v71
	v_cvt_pk_bf16_f32 v71, v76, v77
	global_store_dwordx4 v[80:81], v[68:71], off offset:256
	ds_read2_b32 v[68:69], v148 offset0:128 offset1:144
	s_waitcnt lgkmcnt(0)
; #define PG8_WAIT_V(n) asm volatile("s_waitcnt vmcnt(" #n ")" ::: "memory")
; #define PG8_BAR __builtin_amdgcn_s_barrier()
; __device__ __forceinline__ u32x4 pack8(const f32x4& a, const f32x4& b) { u32x4 w; w.x = pack2(a[0], a[1]); w.y = pack2(a[2], a[3]); w.z = pack2(b[0], b[1]); w.w = pack2(b[2], b[3]); return w; }
; template <class Epi, int LDA, int LDB, int KK>
; __device__ __forceinline__ void gemm_phase(int wv, LAS unsigned char* lds, const Gemm g, const StaticOrder& S, const Epi& E) {
;     ...
;     PG8_WAIT_V(0);
;     if (wr == 0) PG8_BAR;
;     PG8_BAR;
;     __device__ __forceinline__ void operator()(AccT& acc, const pg8::Unit& u, int wr, int wc, int fr, int fq, const LAS float* rs) const {
;     ...
;             for (int m = 0; m < 4; ++m) {
;                 const int row = row0 + ai * 128 + m * 16; const float sc = rsqrtf(rs[ai * 128 + wr * 64 + m * 16 + fr] * (1.0f / D) + EPS);
; #pragma unroll
;                 for (int bj = 0; bj < 2; ++bj) *(u32x4*)(z2 + (size_t)row * NUP + cb + bj * 128) = pack8(acc[ai][bj][m][0] * sc, acc[ai][bj][m][1] * sc);
;             }
	v_fmamk_f32 v68, v68, 0x3a000000, v220
	v_cmp_gt_f32_e32 vcc, s96, v68
	v_mul_f32_e32 v70, 0x4b800000, v68
	s_nop 0
	v_cndmask_b32_e32 v68, v68, v70, vcc
	v_rsq_f32_e32 v68, v68
	s_nop 0
	v_mul_f32_e32 v70, 0x45800000, v68
	v_cndmask_b32_e32 v68, v68, v70, vcc
	v_pk_mul_f32 v[64:65], v[64:65], v[68:69] op_sel_hi:[1,0]
	v_pk_mul_f32 v[70:71], v[62:63], v[68:69] op_sel_hi:[1,0]
	v_pk_mul_f32 v[62:63], v[60:61], v[68:69] op_sel_hi:[1,0]
	v_cvt_pk_bf16_f32 v60, v64, v65
	v_mad_i64_i32 v[64:65], s[6:7], v72, s51, v[124:125]
	v_pk_mul_f32 v[66:67], v[66:67], v[68:69] op_sel_hi:[1,0]
	v_lshl_add_u64 v[64:65], v[64:65], 0, v[126:127]
	v_cvt_pk_bf16_f32 v61, v66, v67
	v_cvt_pk_bf16_f32 v62, v62, v63
	v_cvt_pk_bf16_f32 v63, v70, v71
	global_store_dwordx4 v[64:65], v[60:63], off
	v_pk_mul_f32 v[56:57], v[56:57], v[68:69] op_sel_hi:[1,0]
	v_pk_mul_f32 v[58:59], v[58:59], v[68:69] op_sel_hi:[1,0]
	v_pk_mul_f32 v[60:61], v[54:55], v[68:69] op_sel_hi:[1,0]
	v_pk_mul_f32 v[54:55], v[52:53], v[68:69] op_sel_hi:[1,0]
	v_cvt_pk_bf16_f32 v52, v56, v57
	v_cvt_pk_bf16_f32 v53, v58, v59
	s_nop 0
	v_cvt_pk_bf16_f32 v54, v54, v55
	v_cvt_pk_bf16_f32 v55, v60, v61
	global_store_dwordx4 v[64:65], v[52:55], off offset:256
	s_nop 1
	v_fmamk_f32 v52, v69, 0x3a000000, v220
	v_cmp_gt_f32_e32 vcc, s96, v52
	v_mul_f32_e32 v54, 0x4b800000, v52
	v_add_u32_e32 v53, 0x90, v147
	v_cndmask_b32_e32 v52, v52, v54, vcc
	v_rsq_f32_e32 v52, v52
	s_nop 0
	v_mul_f32_e32 v54, 0x45800000, v52
	v_cndmask_b32_e32 v52, v52, v54, vcc
	v_pk_mul_f32 v[48:49], v[48:49], v[52:53] op_sel_hi:[1,0]
	v_pk_mul_f32 v[54:55], v[46:47], v[52:53] op_sel_hi:[1,0]
	v_pk_mul_f32 v[46:47], v[44:45], v[52:53] op_sel_hi:[1,0]
	v_cvt_pk_bf16_f32 v44, v48, v49
	v_mad_i64_i32 v[48:49], s[6:7], v53, s51, v[124:125]
	v_pk_mul_f32 v[50:51], v[50:51], v[52:53] op_sel_hi:[1,0]
	v_lshl_add_u64 v[48:49], v[48:49], 0, v[126:127]
	v_cvt_pk_bf16_f32 v45, v50, v51
	v_cvt_pk_bf16_f32 v46, v46, v47
	v_cvt_pk_bf16_f32 v47, v54, v55
	global_store_dwordx4 v[48:49], v[44:47], off
	v_pk_mul_f32 v[42:43], v[42:43], v[52:53] op_sel_hi:[1,0]
	v_pk_mul_f32 v[40:41], v[40:41], v[52:53] op_sel_hi:[1,0]
	v_pk_mul_f32 v[44:45], v[38:39], v[52:53] op_sel_hi:[1,0]
	v_pk_mul_f32 v[38:39], v[36:37], v[52:53] op_sel_hi:[1,0]
	v_cvt_pk_bf16_f32 v36, v40, v41
	v_cvt_pk_bf16_f32 v37, v42, v43
	v_add_u32_e32 v40, 0xa0, v147
	v_cvt_pk_bf16_f32 v38, v38, v39
	v_cvt_pk_bf16_f32 v39, v44, v45
	global_store_dwordx4 v[48:49], v[36:39], off offset:256
	ds_read2_b32 v[36:37], v148 offset0:160 offset1:176
	s_waitcnt lgkmcnt(0)
	v_fmamk_f32 v36, v36, 0x3a000000, v220
	v_cmp_gt_f32_e32 vcc, s96, v36
	v_mul_f32_e32 v38, 0x4b800000, v36
	s_nop 0
	v_cndmask_b32_e32 v36, v36, v38, vcc
	v_rsq_f32_e32 v36, v36
	s_nop 0
	v_mul_f32_e32 v38, 0x45800000, v36
	v_cndmask_b32_e32 v36, v36, v38, vcc
	v_pk_mul_f32 v[32:33], v[32:33], v[36:37] op_sel_hi:[1,0]
	v_pk_mul_f32 v[38:39], v[30:31], v[36:37] op_sel_hi:[1,0]
	v_pk_mul_f32 v[30:31], v[28:29], v[36:37] op_sel_hi:[1,0]
	v_cvt_pk_bf16_f32 v28, v32, v33
	v_mad_i64_i32 v[32:33], s[6:7], v40, s51, v[124:125]
	v_pk_mul_f32 v[34:35], v[34:35], v[36:37] op_sel_hi:[1,0]
	v_lshl_add_u64 v[32:33], v[32:33], 0, v[126:127]
	v_cvt_pk_bf16_f32 v29, v34, v35
	v_cvt_pk_bf16_f32 v30, v30, v31
	v_cvt_pk_bf16_f32 v31, v38, v39
	global_store_dwordx4 v[32:33], v[28:31], off
	v_pk_mul_f32 v[24:25], v[24:25], v[36:37] op_sel_hi:[1,0]
	v_pk_mul_f32 v[26:27], v[26:27], v[36:37] op_sel_hi:[1,0]
	v_pk_mul_f32 v[28:29], v[22:23], v[36:37] op_sel_hi:[1,0]
	v_pk_mul_f32 v[22:23], v[20:21], v[36:37] op_sel_hi:[1,0]
	v_cvt_pk_bf16_f32 v20, v24, v25
	v_cvt_pk_bf16_f32 v21, v26, v27
	s_nop 0
	v_cvt_pk_bf16_f32 v22, v22, v23
	v_cvt_pk_bf16_f32 v23, v28, v29
	global_store_dwordx4 v[32:33], v[20:23], off offset:256
	s_nop 1
	v_fmamk_f32 v20, v37, 0x3a000000, v220
	v_cmp_gt_f32_e32 vcc, s96, v20
	v_mul_f32_e32 v22, 0x4b800000, v20
	v_add_u32_e32 v21, 0xb0, v147
	v_cndmask_b32_e32 v20, v20, v22, vcc
	v_rsq_f32_e32 v20, v20
	s_nop 0
	v_mul_f32_e32 v22, 0x45800000, v20
	v_cndmask_b32_e32 v20, v20, v22, vcc
	v_pk_mul_f32 v[16:17], v[16:17], v[20:21] op_sel_hi:[1,0]
	v_pk_mul_f32 v[22:23], v[14:15], v[20:21] op_sel_hi:[1,0]
	v_pk_mul_f32 v[14:15], v[12:13], v[20:21] op_sel_hi:[1,0]
	v_cvt_pk_bf16_f32 v12, v16, v17
	v_mad_i64_i32 v[16:17], s[6:7], v21, s51, v[124:125]
	v_pk_mul_f32 v[18:19], v[18:19], v[20:21] op_sel_hi:[1,0]
	v_lshl_add_u64 v[16:17], v[16:17], 0, v[126:127]
	v_cvt_pk_bf16_f32 v13, v18, v19
	v_cvt_pk_bf16_f32 v14, v14, v15
	v_cvt_pk_bf16_f32 v15, v22, v23
	global_store_dwordx4 v[16:17], v[12:15], off
	s_and_b64 vcc, exec, s[4:5]
	v_pk_mul_f32 v[10:11], v[10:11], v[20:21] op_sel_hi:[1,0]
	v_pk_mul_f32 v[12:13], v[6:7], v[20:21] op_sel_hi:[1,0]
	v_pk_mul_f32 v[6:7], v[4:5], v[20:21] op_sel_hi:[1,0]
	v_pk_mul_f32 v[8:9], v[8:9], v[20:21] op_sel_hi:[1,0]
	v_cvt_pk_bf16_f32 v5, v10, v11
	v_cvt_pk_bf16_f32 v6, v6, v7
	v_cvt_pk_bf16_f32 v7, v12, v13
	s_nop 0
	v_cvt_pk_bf16_f32 v4, v8, v9
	global_store_dwordx4 v[16:17], v[4:7], off offset:256
	s_cbranch_vccz .LBB0_761
.Lup_end:
	s_waitcnt vmcnt(0)
	s_cmpk_gt_u32 s31, 0xff
	s_cbranch_scc1 .LBB0_770
